# diff attention: LDS-DMA issue moved into the unmasked tile body, staggered between wave halves; gemm loop head 64B aligned
# speedup vs baseline: 1.0478x; 1.0038x over previous
; DI int ltid() { int t = threadIdx.x; asm volatile("" : "+v"(t)); return t; }
; template <int DK, int DV, int NM, bool CAUSAL> ...
;     ...
;   const int tid = ltid(), lane = tid & 63, wave = tid >> 6, h = lane >> 5, l31 = lane & 31;
;   const int wq = (NM == 2) ? (wave & 3) : wave;
;   const int mymap = (NM == 2) ? (wave >> 2) : 0;
;   const int q0w = q0 + wq * 32;
;   bf16x8 qf[NKC16];
;   f32x16 o[NDVB];
; #pragma unroll
;   for (int d = 0; d < NDVB; ++d)
; #pragma unroll
;     for (int i = 0; i < 16; ++i) o[d][i] = 0.f;
;   f32x16 lacc;
; #pragma unroll
;   for (int i = 0; i < 16; ++i) lacc[i] = 0.f;
;   u4 onesu; onesu.x = onesu.y = onesu.z = onesu.w = 0x3F803F80u;
;   const bf16x8 ones = __builtin_bit_cast(bf16x8, onesu);
;   const int wu = __builtin_amdgcn_readfirstlane(wave);
;   const int krow = lane >> 4, kslot = lane & 15;
;   const int vrow = lane >> 3, vslot = lane & 7;
;   auto issue = [&](int kt) {
;     char* st = smem + (kt & 3) * STAGE;
; #pragma unroll
;     for (int i = 0; i < 2; ++i) {
;       const int r = (wu * 2 + i) * 4 + krow;
;       const int c = kslot ^ (r & 15);
;       if (KCHV == 16 || c < KCHV)
;         __builtin_amdgcn_global_load_lds((const unsigned*)(Kg + (size_t)(kt * 64 + r) * ldk + c * 8), (unsigned*)(st + (wu * 2 + i) * 1024), 16, 0, 0);
;     }
; #pragma unroll
;     for (int i = 0; i < NVI; ++i) {
;       const int d = (wu * NVI + i) * 8 + vrow;
;       const int c = vslot ^ ((d >> 1) & 7);
;       __builtin_amdgcn_global_load_lds((const unsigned*)(Vt + (size_t)d * ldv + kt * 64 + c * 8), (unsigned*)(st + KBYTES + (wu * NVI + i) * 1024), 16, 0, 0);
;     }
;   };
;   asm volatile("s_waitcnt vmcnt(0)" ::: "memory");
;   __syncthreads();
;   if (0 < nkt) issue(0);
;   if (1 < nkt) issue(1);
;   if (2 < nkt) issue(2);
;   {
;     const bf16_t* qp = Q + (size_t)(wq * 32 + l31) * ldq + mymap * DK + h * 8;
; #pragma unroll
;     for (int kc = 0; kc < NKC16; ++kc) qf[kc] = *(const bf16x8*)(qp + kc * 16);
; #pragma unroll
;     for (int kc = 0; kc < NKC16; ++kc) asm volatile("" : "+v"(qf[kc]));
;   }
.LBB0_90:
	s_xor_b64 s[8:9], s[4:5], -1
	s_or_b32 s4, s16, s30
	s_ashr_i32 s5, s4, 31
	v_and_b32_e32 v162, 3, v159
	s_lshl_b64 s[4:5], s[4:5], 11
	v_lshlrev_b32_e32 v23, 5, v162
	v_and_b32_e32 v24, 31, v158
	s_add_u32 s4, s31, s4
	v_or_b32_e32 v2, v23, v24
	s_addc_u32 s5, s34, s5
	v_ashrrev_i32_e32 v21, 8, v158
	v_lshlrev_b32_e32 v2, 11, v2
	v_mov_b32_e32 v3, v1
	v_and_b32_e32 v161, 63, v158
	v_lshl_add_u64 v[144:145], s[4:5], 0, v[2:3]
	v_lshlrev_b32_e32 v2, 6, v21
	v_lshrrev_b32_e32 v22, 5, v161
	v_ashrrev_i32_e32 v3, 31, v2
	v_lshl_add_u64 v[2:3], v[2:3], 1, v[144:145]
	v_lshlrev_b32_e32 v4, 4, v22
	v_mov_b32_e32 v5, v1
	v_lshl_add_u64 v[2:3], v[2:3], 0, v[4:5]
	flat_load_dwordx4 v[140:143], v[2:3]
	flat_load_dwordx4 v[136:139], v[2:3] offset:32
	flat_load_dwordx4 v[132:135], v[2:3] offset:64
	flat_load_dwordx4 v[128:131], v[2:3] offset:96
	v_mov_b32_e32 v17, v1
	v_add_u32_e32 v20, s61, v11
	v_lshrrev_b32_e32 v25, 1, v158
	v_bfe_u32 v26, v158, 1, 3
	v_lshl_add_u64 v[148:149], s[0:1], 0, v[16:17]
	v_lshlrev_b32_e32 v17, 3, v21
	v_add_u32_e32 v16, 8, v20
	v_ashrrev_i32_e32 v21, 31, v20
	v_or_b32_e32 v169, s16, v23
	v_or_b32_e32 v23, v17, v22
	v_lshlrev_b32_e32 v160, 2, v22
	v_bitop3_b32 v25, v25, v22, 7 bitop3:0x6c
	v_bitop3_b32 v28, v22, v26, 2 bitop3:0x36
	v_bitop3_b32 v29, v22, v26, 4 bitop3:0x36
	v_bitop3_b32 v26, v22, v26, 6 bitop3:0x36
	v_bitop3_b32 v22, v17, v18, v22 bitop3:0x36
	v_ashrrev_i32_e32 v17, 31, v16
	v_and_b32_e32 v27, 7, v12
	v_lshlrev_b64 v[20:21], 12, v[20:21]
	v_lshlrev_b64 v[16:17], 12, v[16:17]
	v_mov_b32_e32 v14, v1
	v_mov_b32_e32 v15, v1
	v_lshlrev_b32_e32 v170, 8, v24
	v_lshlrev_b32_e32 v168, 7, v24
	v_or_b32_e32 v165, v169, v24
	v_lshlrev_b32_e32 v174, 4, v22
	v_bitop3_b32 v22, v23, v18, 2 bitop3:0x36
	v_bitop3_b32 v24, v23, v18, 4 bitop3:0x36
	v_bitop3_b32 v18, v23, v18, 6 bitop3:0x36
	v_lshl_or_b32 v20, v19, 4, v20
	s_addk_i32 s16, 0x80
	v_lshl_or_b32 v16, v27, 4, v16
	v_lshl_add_u64 v[146:147], s[0:1], 0, v[0:1]
	v_add_u32_e32 v171, s17, v10
	v_mov_b32_e32 v0, v1
	v_mov_b32_e32 v2, v1
	v_mov_b32_e32 v3, v1
	v_mov_b32_e32 v4, v1
	v_mov_b32_e32 v6, v1
	v_mov_b32_e32 v7, v1
	v_mov_b32_e32 v8, v1
	v_mov_b32_e32 v9, v1
	v_mov_b32_e32 v10, v1
	v_mov_b32_e32 v11, v1
	v_mov_b32_e32 v12, v1
	v_mov_b32_e32 v13, v1
	v_lshlrev_b32_e32 v167, 4, v25
	v_lshlrev_b32_e32 v166, 4, v28
	v_lshlrev_b32_e32 v164, 4, v29
	v_lshlrev_b32_e32 v163, 4, v26
	v_lshlrev_b32_e32 v175, 4, v22
	v_lshlrev_b32_e32 v173, 4, v24
	v_lshlrev_b32_e32 v172, 4, v18
	v_lshl_add_u64 v[152:153], s[6:7], 0, v[20:21]
	s_lshr_b32 s61, s16, 6
	v_lshl_add_u64 v[154:155], s[6:7], 0, v[16:17]
	v_mov_b64_e32 v[30:31], v[14:15]
	v_mov_b64_e32 v[46:47], v[14:15]
	v_mov_b64_e32 v[62:63], v[14:15]
	v_mov_b64_e32 v[78:79], v[14:15]
	v_mov_b64_e32 v[94:95], v[14:15]
	v_or_b32_e32 v176, 31, v169
	s_add_i32 s62, s61, -2
	s_mov_b32 s63, 0
	s_mov_b32 s64, 0
	v_mov_b64_e32 v[28:29], v[12:13]
	v_mov_b64_e32 v[26:27], v[10:11]
	v_mov_b64_e32 v[24:25], v[8:9]
	v_mov_b64_e32 v[22:23], v[6:7]
	v_mov_b64_e32 v[20:21], v[4:5]
	v_mov_b64_e32 v[18:19], v[2:3]
	v_mov_b64_e32 v[16:17], v[0:1]
	v_mov_b64_e32 v[44:45], v[12:13]
	v_mov_b64_e32 v[42:43], v[10:11]
	v_mov_b64_e32 v[40:41], v[8:9]
	v_mov_b64_e32 v[38:39], v[6:7]
	v_mov_b64_e32 v[36:37], v[4:5]
	v_mov_b64_e32 v[34:35], v[2:3]
	v_mov_b64_e32 v[32:33], v[0:1]
	v_mov_b64_e32 v[60:61], v[12:13]
	v_mov_b64_e32 v[58:59], v[10:11]
	v_mov_b64_e32 v[56:57], v[8:9]
	v_mov_b64_e32 v[54:55], v[6:7]
	v_mov_b64_e32 v[52:53], v[4:5]
	v_mov_b64_e32 v[50:51], v[2:3]
	v_mov_b64_e32 v[48:49], v[0:1]
	v_mov_b64_e32 v[76:77], v[12:13]
	v_mov_b64_e32 v[74:75], v[10:11]
	v_mov_b64_e32 v[72:73], v[8:9]
	v_mov_b64_e32 v[70:71], v[6:7]
	v_mov_b64_e32 v[68:69], v[4:5]
	v_mov_b64_e32 v[66:67], v[2:3]
	v_mov_b64_e32 v[64:65], v[0:1]
	s_mov_b32 s65, 0
	v_mov_b64_e32 v[92:93], v[12:13]
	v_mov_b64_e32 v[90:91], v[10:11]
	v_mov_b64_e32 v[88:89], v[8:9]
	v_mov_b64_e32 v[86:87], v[6:7]
	v_mov_b64_e32 v[84:85], v[4:5]
	v_mov_b64_e32 v[82:83], v[2:3]
	v_mov_b64_e32 v[80:81], v[0:1]
	v_mov_b32_e32 v248, v1
	v_mov_b32_e32 v249, v1
	v_readfirstlane_b32 s100, v169
	v_readfirstlane_b32 s101, v195
	s_nop 3
	s_lshr_b32 s101, s101, 8
	s_waitcnt vmcnt(0) lgkmcnt(0)
	s_cmp_ge_u32 s65, s62
	s_mov_b64 s[4:5], -1
	s_cbranch_scc0 .LBB0_93
	s_branch .LBB0_92

; template <int DK, int DV, int NM, bool CAUSAL> ...
;     ...
;   for (int kt = 0; kt < nkt; ++kt) {
;     if (kt + 2 < nkt) asm volatile("s_waitcnt vmcnt(%0)" ::"n"(2 * NLD) : "memory");
;     else if (kt + 1 < nkt) asm volatile("s_waitcnt vmcnt(%0)" ::"n"(NLD) : "memory");
;     else asm volatile("s_waitcnt vmcnt(0)" ::: "memory");
;     asm volatile("s_waitcnt lgkmcnt(0)" ::: "memory");
;     __builtin_amdgcn_s_barrier();
;     if (kt + 3 < nkt) issue(kt + 3);
;     const bool skip = CAUSAL && (kt * 64 > q0w + 31);
;     if (!skip) {
;       const char* base = smem + (kt & 3) * STAGE;
;       f32x16 s[2];
; #pragma unroll
;       for (int sb = 0; sb < 2; ++sb) {
; #pragma unroll
;         for (int i = 0; i < 16; ++i) s[sb][i] = 0.f;
;         const char* pk = base + (sb * 32 + l31) * 256;
; #pragma unroll
;         for (int kc = 0; kc < NKC16; ++kc) {
;           const bf16x8 a = *(const bf16x8*)(pk + (((mymap * (DK / 8) + kc * 2 + h) ^ (l31 & 15)) * 16));
;           s[sb] = MFMA(a, qf[kc], s[sb]);
;         }
;         __builtin_amdgcn_sched_barrier(0);
;       }
;       const bool need_mask = CAUSAL && (kt * 64 + 63 > q0w);
;       const char* pv = base + KBYTES + l31 * 128;
;       const int vsw = (l31 >> 1) & 7;
;       bf16x8 pf[4];
;       auto expo = [&](int sb) {
; #pragma unroll
;         for (int i = 0; i < 16; ++i) {
;           float pz = __builtin_amdgcn_exp2f(s[sb][i]);
;           if (need_mask) {
;             const int key = kt * 64 + sb * 32 + crow(i, h);
;             if (key > q0w + l31) pz = 0.f;
;           }
;           s[sb][i] = pz;
;         }
; #pragma unroll
;         for (int k2 = 0; k2 < 2; ++k2) {
;           u4 pu;
;           pu.x = pack2(s[sb][k2 * 8 + 0], s[sb][k2 * 8 + 1]);
;           pu.y = pack2(s[sb][k2 * 8 + 2], s[sb][k2 * 8 + 3]);
;           pu.z = pack2(s[sb][k2 * 8 + 4], s[sb][k2 * 8 + 5]);
;           pu.w = pack2(s[sb][k2 * 8 + 6], s[sb][k2 * 8 + 7]);
;           pf[sb * 2 + k2] = __builtin_bit_cast(bf16x8, pu);
;         }
;       };
;       auto pvmm = [&](int ks) {
;         lacc = MFMA(ones, pf[ks], lacc);
; #pragma unroll
;         for (int d = 0; d < NDVB; ++d) {
;           const u4 au = *(const u4*)(pv + d * 32 * 128 + (((ks * 2 + h) ^ vsw) * 16));
;           o[d] = MFMA(__builtin_bit_cast(bf16x8, au), pf[ks], o[d]);
;         }
;       };
;       expo(0);
;       pvmm(0); pvmm(1);
;       expo(1);
.LBB0_95:
	s_waitcnt lgkmcnt(0)
	s_add_i32 s4, s65, 3
	s_cmp_ge_u32 s4, s61
	s_barrier
	s_cbranch_scc1 .LBB0_97
	s_add_i32 s4, s63, 63
	s_cmp_le_u32 s4, s100
	s_cbranch_scc0 .Lmy_d96
	s_cmp_eq_u32 s101, 1
	s_cbranch_scc1 .Lmy_dlate
	s_and_b32 s4, s64, 0x18000
	v_or_b32_e32 v0, s4, v170
	v_add_u32_e32 v6, v0, v174
	v_add_u32_e32 v7, v0, v175
	v_add_u32_e32 v8, v0, v173
	v_add_u32_e32 v9, v0, v172
	ds_read_b128 v[212:215], v6
	ds_read_b128 v[216:219], v7
	ds_read_b128 v[220:223], v8
	ds_read_b128 v[224:227], v9
	ds_read_b128 v[228:231], v6 offset:8192
	ds_read_b128 v[232:235], v7 offset:8192
	ds_read_b128 v[236:239], v8 offset:8192
	ds_read_b128 v[240:243], v9 offset:8192
	v_or_b32_e32 v0, s4, v168
	v_add_u32_e32 v10, v0, v167
	v_add_u32_e32 v11, v0, v166
	v_add_u32_e32 v12, v0, v164
	v_add_u32_e32 v13, v0, v163
	v_add_u32_e32 v0, s63, v171
	v_add_u32_e32 v6, 0xc0, v0
	v_add_u32_e32 v8, 0xc4, v0
	v_ashrrev_i32_e32 v7, 31, v6
	v_ashrrev_i32_e32 v9, 31, v8
	v_lshlrev_b64 v[6:7], 11, v[6:7]
	v_lshlrev_b64 v[8:9], 11, v[8:9]
	s_add_i32 s4, s64, 0x18000
	s_and_b32 s4, s4, 0x18000
	v_lshl_add_u64 v[6:7], v[148:149], 0, v[6:7]
	v_lshl_add_u64 v[8:9], v[146:147], 0, v[8:9]
	s_add_i32 s5, s4, s35
	s_add_i32 s4, s4, s60
	s_waitcnt lgkmcnt(7)
	v_mfma_f32_32x32x16_bf16 v[112:127], v[212:215], v[140:143], 0
	s_mov_b32 m0, s5
	s_waitcnt lgkmcnt(6)
	v_mfma_f32_32x32x16_bf16 v[112:127], v[216:219], v[136:139], v[112:127]
	global_load_lds_dwordx4 v[6:7], off
	s_waitcnt lgkmcnt(5)
	v_mfma_f32_32x32x16_bf16 v[112:127], v[220:223], v[132:135], v[112:127]
	s_mov_b32 m0, s4
	s_waitcnt lgkmcnt(4)
	v_mfma_f32_32x32x16_bf16 v[112:127], v[224:227], v[128:131], v[112:127]
	global_load_lds_dwordx4 v[8:9], off
	ds_read_b128 v[212:215], v10 offset:16384
	ds_read_b128 v[216:219], v10 offset:20480
	s_waitcnt lgkmcnt(5)
	v_mfma_f32_32x32x16_bf16 v[96:111], v[228:231], v[140:143], 0
	s_add_i32 m0, s5, 0x4000
	ds_read_b128 v[220:223], v10 offset:24576
	ds_read_b128 v[224:227], v10 offset:28672
	s_waitcnt lgkmcnt(6)
	v_mfma_f32_32x32x16_bf16 v[96:111], v[232:235], v[136:139], v[96:111]
	global_load_lds_dwordx4 v[152:153], off
	s_waitcnt lgkmcnt(5)
	v_mfma_f32_32x32x16_bf16 v[96:111], v[236:239], v[132:135], v[96:111]
	s_add_i32 m0, s4, 0x4000
	s_waitcnt lgkmcnt(4)
	v_mfma_f32_32x32x16_bf16 v[96:111], v[240:243], v[128:131], v[96:111]
	global_load_lds_dwordx4 v[154:155], off
	ds_read_b128 v[228:231], v11 offset:16384
	ds_read_b128 v[232:235], v11 offset:20480
	ds_read_b128 v[236:239], v11 offset:24576
	ds_read_b128 v[240:243], v11 offset:28672
	v_exp_f32_e32 v112, v112
	v_exp_f32_e32 v113, v113
	v_exp_f32_e32 v114, v114
	v_exp_f32_e32 v115, v115
	v_exp_f32_e32 v116, v116
	v_exp_f32_e32 v117, v117
	v_exp_f32_e32 v118, v118
	v_exp_f32_e32 v119, v119
	v_add_f32_e32 v248, v248, v112
	v_add_f32_e32 v249, v249, v113
	v_add_f32_e32 v248, v248, v114
	v_add_f32_e32 v249, v249, v115
	v_add_f32_e32 v248, v248, v116
	v_add_f32_e32 v249, v249, v117
	v_add_f32_e32 v248, v248, v118
	v_add_f32_e32 v249, v249, v119
	v_cvt_pk_bf16_f32 v186, v112, v113
	v_cvt_pk_bf16_f32 v187, v114, v115
	v_cvt_pk_bf16_f32 v188, v116, v117
	v_cvt_pk_bf16_f32 v189, v118, v119
	s_nop 0
	s_waitcnt lgkmcnt(7)
	v_mfma_f32_32x32x16_bf16 v[64:79], v[212:215], v[186:189], v[64:79]
	ds_read_b128 v[212:215], v12 offset:16384
	v_exp_f32_e32 v120, v120
	v_exp_f32_e32 v121, v121
	v_exp_f32_e32 v122, v122
	v_exp_f32_e32 v123, v123
	v_exp_f32_e32 v124, v124
	s_waitcnt lgkmcnt(7)
	v_mfma_f32_32x32x16_bf16 v[48:63], v[216:219], v[186:189], v[48:63]
	ds_read_b128 v[216:219], v12 offset:20480
	v_exp_f32_e32 v125, v125
	v_exp_f32_e32 v126, v126
	v_exp_f32_e32 v127, v127
	v_add_f32_e32 v248, v248, v120
	v_add_f32_e32 v249, v249, v121
	s_waitcnt lgkmcnt(7)
	v_mfma_f32_32x32x16_bf16 v[32:47], v[220:223], v[186:189], v[32:47]
	ds_read_b128 v[220:223], v12 offset:24576
	v_add_f32_e32 v248, v248, v122
	v_add_f32_e32 v249, v249, v123
	v_add_f32_e32 v248, v248, v124
	v_add_f32_e32 v249, v249, v125
	v_add_f32_e32 v248, v248, v126
	s_waitcnt lgkmcnt(7)
	v_mfma_f32_32x32x16_bf16 v[16:31], v[224:227], v[186:189], v[16:31]
	ds_read_b128 v[224:227], v12 offset:28672
	v_add_f32_e32 v249, v249, v127
	v_cvt_pk_bf16_f32 v190, v120, v121
	v_cvt_pk_bf16_f32 v191, v122, v123
	v_cvt_pk_bf16_f32 v192, v124, v125
	v_cvt_pk_bf16_f32 v193, v126, v127
	s_nop 0
	s_waitcnt lgkmcnt(7)
	v_mfma_f32_32x32x16_bf16 v[64:79], v[228:231], v[190:193], v[64:79]
	ds_read_b128 v[228:231], v13 offset:16384
	v_exp_f32_e32 v96, v96
	v_exp_f32_e32 v97, v97
	v_exp_f32_e32 v98, v98
	v_exp_f32_e32 v99, v99
	v_exp_f32_e32 v100, v100
	s_waitcnt lgkmcnt(7)
	v_mfma_f32_32x32x16_bf16 v[48:63], v[232:235], v[190:193], v[48:63]
	ds_read_b128 v[232:235], v13 offset:20480
	v_exp_f32_e32 v101, v101
	v_exp_f32_e32 v102, v102
	v_exp_f32_e32 v103, v103
	v_add_f32_e32 v248, v248, v96
	v_add_f32_e32 v249, v249, v97
	s_waitcnt lgkmcnt(7)
	v_mfma_f32_32x32x16_bf16 v[32:47], v[236:239], v[190:193], v[32:47]
	ds_read_b128 v[236:239], v13 offset:24576
	v_add_f32_e32 v248, v248, v98
	v_add_f32_e32 v249, v249, v99
	v_add_f32_e32 v248, v248, v100
	v_add_f32_e32 v249, v249, v101
	v_add_f32_e32 v248, v248, v102
	s_waitcnt lgkmcnt(7)
	v_mfma_f32_32x32x16_bf16 v[16:31], v[240:243], v[190:193], v[16:31]
	ds_read_b128 v[240:243], v13 offset:28672
	v_add_f32_e32 v249, v249, v103
	v_cvt_pk_bf16_f32 v244, v96, v97
	v_cvt_pk_bf16_f32 v245, v98, v99
	v_cvt_pk_bf16_f32 v246, v100, v101
	v_cvt_pk_bf16_f32 v247, v102, v103
	s_nop 0
	s_waitcnt lgkmcnt(7)
	v_mfma_f32_32x32x16_bf16 v[64:79], v[212:215], v[244:247], v[64:79]
	v_exp_f32_e32 v104, v104
	v_exp_f32_e32 v105, v105
	v_exp_f32_e32 v106, v106
	v_exp_f32_e32 v107, v107
	v_exp_f32_e32 v108, v108
	s_waitcnt lgkmcnt(6)
	v_mfma_f32_32x32x16_bf16 v[48:63], v[216:219], v[244:247], v[48:63]
	v_exp_f32_e32 v109, v109
	v_exp_f32_e32 v110, v110
	v_exp_f32_e32 v111, v111
	v_add_f32_e32 v248, v248, v104
	v_add_f32_e32 v249, v249, v105
	s_waitcnt lgkmcnt(5)
	v_mfma_f32_32x32x16_bf16 v[32:47], v[220:223], v[244:247], v[32:47]
	v_add_f32_e32 v248, v248, v106
	v_add_f32_e32 v249, v249, v107
	v_add_f32_e32 v248, v248, v108
	v_add_f32_e32 v249, v249, v109
	v_add_f32_e32 v248, v248, v110
	s_waitcnt lgkmcnt(4)
	v_mfma_f32_32x32x16_bf16 v[16:31], v[224:227], v[244:247], v[16:31]
	v_add_f32_e32 v249, v249, v111
	v_cvt_pk_bf16_f32 v2, v104, v105
	v_cvt_pk_bf16_f32 v3, v106, v107
	v_cvt_pk_bf16_f32 v4, v108, v109
	v_cvt_pk_bf16_f32 v5, v110, v111
	s_nop 0
	s_waitcnt lgkmcnt(3)
	v_mfma_f32_32x32x16_bf16 v[64:79], v[228:231], v[2:5], v[64:79]
	s_waitcnt lgkmcnt(2)
	v_mfma_f32_32x32x16_bf16 v[48:63], v[232:235], v[2:5], v[48:63]
	s_waitcnt lgkmcnt(1)
	v_mfma_f32_32x32x16_bf16 v[32:47], v[236:239], v[2:5], v[32:47]
	s_waitcnt lgkmcnt(0)
	v_mfma_f32_32x32x16_bf16 v[16:31], v[240:243], v[2:5], v[16:31]
	s_branch .LBB0_99
; template <int DK, int DV, int NM, bool CAUSAL> ...
;     ...
;   for (int kt = 0; kt < nkt; ++kt) {
;     if (kt + 2 < nkt) asm volatile("s_waitcnt vmcnt(%0)" ::"n"(2 * NLD) : "memory");
;     else if (kt + 1 < nkt) asm volatile("s_waitcnt vmcnt(%0)" ::"n"(NLD) : "memory");
;     else asm volatile("s_waitcnt vmcnt(0)" ::: "memory");
;     asm volatile("s_waitcnt lgkmcnt(0)" ::: "memory");
;     __builtin_amdgcn_s_barrier();
;     if (kt + 3 < nkt) issue(kt + 3);
;     const bool skip = CAUSAL && (kt * 64 > q0w + 31);
;     if (!skip) {
;       const char* base = smem + (kt & 3) * STAGE;
;       f32x16 s[2];
; #pragma unroll
;       for (int sb = 0; sb < 2; ++sb) {
; #pragma unroll
;         for (int i = 0; i < 16; ++i) s[sb][i] = 0.f;
;         const char* pk = base + (sb * 32 + l31) * 256;
; #pragma unroll
;         for (int kc = 0; kc < NKC16; ++kc) {
;           const bf16x8 a = *(const bf16x8*)(pk + (((mymap * (DK / 8) + kc * 2 + h) ^ (l31 & 15)) * 16));
;           s[sb] = MFMA(a, qf[kc], s[sb]);
;         }
;         __builtin_amdgcn_sched_barrier(0);
;       }
;       const bool need_mask = CAUSAL && (kt * 64 + 63 > q0w);
;       const char* pv = base + KBYTES + l31 * 128;
;       const int vsw = (l31 >> 1) & 7;
;       bf16x8 pf[4];
;       auto expo = [&](int sb) {
; #pragma unroll
;         for (int i = 0; i < 16; ++i) {
;           float pz = __builtin_amdgcn_exp2f(s[sb][i]);
;           if (need_mask) {
;             const int key = kt * 64 + sb * 32 + crow(i, h);
;             if (key > q0w + l31) pz = 0.f;
;           }
;           s[sb][i] = pz;
;         }
; #pragma unroll
;         for (int k2 = 0; k2 < 2; ++k2) {
;           u4 pu;
;           pu.x = pack2(s[sb][k2 * 8 + 0], s[sb][k2 * 8 + 1]);
;           pu.y = pack2(s[sb][k2 * 8 + 2], s[sb][k2 * 8 + 3]);
;           pu.z = pack2(s[sb][k2 * 8 + 4], s[sb][k2 * 8 + 5]);
;           pu.w = pack2(s[sb][k2 * 8 + 6], s[sb][k2 * 8 + 7]);
;           pf[sb * 2 + k2] = __builtin_bit_cast(bf16x8, pu);
;         }
;       };
;       auto pvmm = [&](int ks) {
;         lacc = MFMA(ones, pf[ks], lacc);
; #pragma unroll
;         for (int d = 0; d < NDVB; ++d) {
;           const u4 au = *(const u4*)(pv + d * 32 * 128 + (((ks * 2 + h) ^ vsw) * 16));
;           o[d] = MFMA(__builtin_bit_cast(bf16x8, au), pf[ks], o[d]);
;         }
;       };
;       expo(0);
;       pvmm(0); pvmm(1);
;       expo(1);
.Lmy_dlate:
	s_and_b32 s4, s64, 0x18000
	v_or_b32_e32 v0, s4, v170
	v_add_u32_e32 v6, v0, v174
	v_add_u32_e32 v7, v0, v175
	v_add_u32_e32 v8, v0, v173
	v_add_u32_e32 v9, v0, v172
	ds_read_b128 v[212:215], v6
	ds_read_b128 v[216:219], v7
	ds_read_b128 v[220:223], v8
	ds_read_b128 v[224:227], v9
	ds_read_b128 v[228:231], v6 offset:8192
	ds_read_b128 v[232:235], v7 offset:8192
	ds_read_b128 v[236:239], v8 offset:8192
	ds_read_b128 v[240:243], v9 offset:8192
	v_or_b32_e32 v0, s4, v168
	v_add_u32_e32 v10, v0, v167
	v_add_u32_e32 v11, v0, v166
	v_add_u32_e32 v12, v0, v164
	v_add_u32_e32 v13, v0, v163
	s_waitcnt lgkmcnt(7)
	v_mfma_f32_32x32x16_bf16 v[112:127], v[212:215], v[140:143], 0
	s_waitcnt lgkmcnt(6)
	v_mfma_f32_32x32x16_bf16 v[112:127], v[216:219], v[136:139], v[112:127]
	s_waitcnt lgkmcnt(5)
	v_mfma_f32_32x32x16_bf16 v[112:127], v[220:223], v[132:135], v[112:127]
	s_waitcnt lgkmcnt(4)
	v_mfma_f32_32x32x16_bf16 v[112:127], v[224:227], v[128:131], v[112:127]
	ds_read_b128 v[212:215], v10 offset:16384
	ds_read_b128 v[216:219], v10 offset:20480
	s_waitcnt lgkmcnt(5)
	v_mfma_f32_32x32x16_bf16 v[96:111], v[228:231], v[140:143], 0
	ds_read_b128 v[220:223], v10 offset:24576
	ds_read_b128 v[224:227], v10 offset:28672
	s_waitcnt lgkmcnt(6)
	v_mfma_f32_32x32x16_bf16 v[96:111], v[232:235], v[136:139], v[96:111]
	s_waitcnt lgkmcnt(5)
	v_mfma_f32_32x32x16_bf16 v[96:111], v[236:239], v[132:135], v[96:111]
	s_waitcnt lgkmcnt(4)
	v_mfma_f32_32x32x16_bf16 v[96:111], v[240:243], v[128:131], v[96:111]
	ds_read_b128 v[228:231], v11 offset:16384
	ds_read_b128 v[232:235], v11 offset:20480
	ds_read_b128 v[236:239], v11 offset:24576
	ds_read_b128 v[240:243], v11 offset:28672
	v_exp_f32_e32 v112, v112
	v_exp_f32_e32 v113, v113
	v_exp_f32_e32 v114, v114
	v_exp_f32_e32 v115, v115
	v_exp_f32_e32 v116, v116
	v_exp_f32_e32 v117, v117
	v_exp_f32_e32 v118, v118
	v_exp_f32_e32 v119, v119
	v_add_f32_e32 v248, v248, v112
	v_add_f32_e32 v249, v249, v113
	v_add_f32_e32 v248, v248, v114
	v_add_f32_e32 v249, v249, v115
	v_add_f32_e32 v248, v248, v116
	v_add_f32_e32 v249, v249, v117
	v_add_f32_e32 v248, v248, v118
	v_add_f32_e32 v249, v249, v119
	v_cvt_pk_bf16_f32 v186, v112, v113
	v_cvt_pk_bf16_f32 v187, v114, v115
	v_cvt_pk_bf16_f32 v188, v116, v117
	v_cvt_pk_bf16_f32 v189, v118, v119
	s_nop 0
	v_add_u32_e32 v0, s63, v171
	v_add_u32_e32 v6, 0xc0, v0
	v_add_u32_e32 v8, 0xc4, v0
	v_ashrrev_i32_e32 v7, 31, v6
	v_ashrrev_i32_e32 v9, 31, v8
	v_lshlrev_b64 v[6:7], 11, v[6:7]
	v_lshlrev_b64 v[8:9], 11, v[8:9]
	s_add_i32 s4, s64, 0x18000
	s_and_b32 s4, s4, 0x18000
	v_lshl_add_u64 v[6:7], v[148:149], 0, v[6:7]
	v_lshl_add_u64 v[8:9], v[146:147], 0, v[8:9]
	s_add_i32 s5, s4, s35
	s_add_i32 s4, s4, s60
	s_waitcnt lgkmcnt(7)
	v_mfma_f32_32x32x16_bf16 v[64:79], v[212:215], v[186:189], v[64:79]
	ds_read_b128 v[212:215], v12 offset:16384
	v_exp_f32_e32 v120, v120
	v_exp_f32_e32 v121, v121
	v_exp_f32_e32 v122, v122
	v_exp_f32_e32 v123, v123
	v_exp_f32_e32 v124, v124
	s_waitcnt lgkmcnt(7)
	v_mfma_f32_32x32x16_bf16 v[48:63], v[216:219], v[186:189], v[48:63]
	ds_read_b128 v[216:219], v12 offset:20480
	v_exp_f32_e32 v125, v125
	v_exp_f32_e32 v126, v126
	v_exp_f32_e32 v127, v127
	v_add_f32_e32 v248, v248, v120
	v_add_f32_e32 v249, v249, v121
	s_waitcnt lgkmcnt(7)
	v_mfma_f32_32x32x16_bf16 v[32:47], v[220:223], v[186:189], v[32:47]
	ds_read_b128 v[220:223], v12 offset:24576
	v_add_f32_e32 v248, v248, v122
	v_add_f32_e32 v249, v249, v123
	v_add_f32_e32 v248, v248, v124
	v_add_f32_e32 v249, v249, v125
	v_add_f32_e32 v248, v248, v126
	s_waitcnt lgkmcnt(7)
	v_mfma_f32_32x32x16_bf16 v[16:31], v[224:227], v[186:189], v[16:31]
	ds_read_b128 v[224:227], v12 offset:28672
	v_add_f32_e32 v249, v249, v127
	v_cvt_pk_bf16_f32 v190, v120, v121
	v_cvt_pk_bf16_f32 v191, v122, v123
	v_cvt_pk_bf16_f32 v192, v124, v125
	v_cvt_pk_bf16_f32 v193, v126, v127
	s_nop 0
	s_mov_b32 m0, s5
	s_waitcnt lgkmcnt(7)
	v_mfma_f32_32x32x16_bf16 v[64:79], v[228:231], v[190:193], v[64:79]
	global_load_lds_dwordx4 v[6:7], off
	ds_read_b128 v[228:231], v13 offset:16384
	v_exp_f32_e32 v96, v96
	v_exp_f32_e32 v97, v97
	v_exp_f32_e32 v98, v98
	v_exp_f32_e32 v99, v99
	v_exp_f32_e32 v100, v100
	s_mov_b32 m0, s4
	s_waitcnt lgkmcnt(7)
	v_mfma_f32_32x32x16_bf16 v[48:63], v[232:235], v[190:193], v[48:63]
	global_load_lds_dwordx4 v[8:9], off
	ds_read_b128 v[232:235], v13 offset:20480
	v_exp_f32_e32 v101, v101
	v_exp_f32_e32 v102, v102
	v_exp_f32_e32 v103, v103
	v_add_f32_e32 v248, v248, v96
	v_add_f32_e32 v249, v249, v97
	s_add_i32 m0, s5, 0x4000
	s_waitcnt lgkmcnt(7)
	v_mfma_f32_32x32x16_bf16 v[32:47], v[236:239], v[190:193], v[32:47]
	global_load_lds_dwordx4 v[152:153], off
	ds_read_b128 v[236:239], v13 offset:24576
	v_add_f32_e32 v248, v248, v98
	v_add_f32_e32 v249, v249, v99
	v_add_f32_e32 v248, v248, v100
	v_add_f32_e32 v249, v249, v101
	v_add_f32_e32 v248, v248, v102
	s_add_i32 m0, s4, 0x4000
	s_waitcnt lgkmcnt(7)
	v_mfma_f32_32x32x16_bf16 v[16:31], v[240:243], v[190:193], v[16:31]
	global_load_lds_dwordx4 v[154:155], off
	ds_read_b128 v[240:243], v13 offset:28672
	v_add_f32_e32 v249, v249, v103
	v_cvt_pk_bf16_f32 v244, v96, v97
	v_cvt_pk_bf16_f32 v245, v98, v99
	v_cvt_pk_bf16_f32 v246, v100, v101
	v_cvt_pk_bf16_f32 v247, v102, v103
	s_nop 0
	s_waitcnt lgkmcnt(7)
	v_mfma_f32_32x32x16_bf16 v[64:79], v[212:215], v[244:247], v[64:79]
	v_exp_f32_e32 v104, v104
	v_exp_f32_e32 v105, v105
	v_exp_f32_e32 v106, v106
	v_exp_f32_e32 v107, v107
	v_exp_f32_e32 v108, v108
	s_waitcnt lgkmcnt(6)
	v_mfma_f32_32x32x16_bf16 v[48:63], v[216:219], v[244:247], v[48:63]
	v_exp_f32_e32 v109, v109
	v_exp_f32_e32 v110, v110
	v_exp_f32_e32 v111, v111
	v_add_f32_e32 v248, v248, v104
	v_add_f32_e32 v249, v249, v105
	s_waitcnt lgkmcnt(5)
	v_mfma_f32_32x32x16_bf16 v[32:47], v[220:223], v[244:247], v[32:47]
	v_add_f32_e32 v248, v248, v106
	v_add_f32_e32 v249, v249, v107
	v_add_f32_e32 v248, v248, v108
	v_add_f32_e32 v249, v249, v109
	v_add_f32_e32 v248, v248, v110
	s_waitcnt lgkmcnt(4)
	v_mfma_f32_32x32x16_bf16 v[16:31], v[224:227], v[244:247], v[16:31]
	v_add_f32_e32 v249, v249, v111
	v_cvt_pk_bf16_f32 v2, v104, v105
	v_cvt_pk_bf16_f32 v3, v106, v107
	v_cvt_pk_bf16_f32 v4, v108, v109
	v_cvt_pk_bf16_f32 v5, v110, v111
	s_nop 0
	s_waitcnt lgkmcnt(3)
	v_mfma_f32_32x32x16_bf16 v[64:79], v[228:231], v[2:5], v[64:79]
	s_waitcnt lgkmcnt(2)
	v_mfma_f32_32x32x16_bf16 v[48:63], v[232:235], v[2:5], v[48:63]
	s_waitcnt lgkmcnt(1)
	v_mfma_f32_32x32x16_bf16 v[32:47], v[236:239], v[2:5], v[32:47]
	s_waitcnt lgkmcnt(0)
	v_mfma_f32_32x32x16_bf16 v[16:31], v[240:243], v[2:5], v[16:31]
	s_branch .LBB0_99
; template <int DK, int DV, int NM, bool CAUSAL> ...
;     ...
;   auto issue = [&](int kt) {
;     char* st = smem + (kt & 3) * STAGE;
; #pragma unroll
;     for (int i = 0; i < 2; ++i) {
;       const int r = (wu * 2 + i) * 4 + krow;
;       const int c = kslot ^ (r & 15);
;       if (KCHV == 16 || c < KCHV)
;         __builtin_amdgcn_global_load_lds((const unsigned*)(Kg + (size_t)(kt * 64 + r) * ldk + c * 8), (unsigned*)(st + (wu * 2 + i) * 1024), 16, 0, 0);
;     }
; #pragma unroll
;     for (int i = 0; i < NVI; ++i) {
;       const int d = (wu * NVI + i) * 8 + vrow;
;       const int c = vslot ^ ((d >> 1) & 7);
;       __builtin_amdgcn_global_load_lds((const unsigned*)(Vt + (size_t)d * ldv + kt * 64 + c * 8), (unsigned*)(st + KBYTES + (wu * NVI + i) * 1024), 16, 0, 0);
;     }
;   };
.Lmy_d96:
	v_add_u32_e32 v0, s63, v171
	s_add_i32 s4, s64, 0x18000
	v_add_u32_e32 v2, 0xc0, v0
	s_and_b32 s4, s4, 0x18000
	v_ashrrev_i32_e32 v3, 31, v2
	v_lshlrev_b64 v[2:3], 11, v[2:3]
	s_add_i32 s5, s4, s35
	v_lshl_add_u64 v[2:3], v[148:149], 0, v[2:3]
	s_mov_b32 m0, s5
	s_add_i32 s4, s4, s60
	global_load_lds_dwordx4 v[2:3], off
	v_add_u32_e32 v2, 0xc4, v0
	v_ashrrev_i32_e32 v3, 31, v2
	v_lshlrev_b64 v[2:3], 11, v[2:3]
	v_lshl_add_u64 v[2:3], v[146:147], 0, v[2:3]
	s_mov_b32 m0, s4
	s_nop 0
	global_load_lds_dwordx4 v[2:3], off
	s_add_i32 m0, s5, 0x4000
	s_nop 0
	global_load_lds_dwordx4 v[152:153], off
	s_add_i32 m0, s4, 0x4000
	s_nop 0
	global_load_lds_dwordx4 v[154:155], off
